# NSA selected-branch epilogue: scratch read-modify-write loads hoisted with counted waits
# speedup vs baseline: 1.1692x; 1.0018x over previous
; DI unsigned pk2(float a, float b) { f2_t v = {a, b}; bf2_t r = __builtin_convertvector(v, bf2_t); return __builtin_bit_cast(unsigned, r); }
; DI float bflo(unsigned u) { return (float)__builtin_bit_cast(bf2_t, u)[0]; }
; DI float bfhi(unsigned u) { return (float)__builtin_bit_cast(bf2_t, u)[1]; }
; #define NSA_GATE(c_, nb_) sigmoidf_(bf2f(zb[(size_t)qpos[nb_] * ZS + GATEC + (c_) * 8 + head]))
; DI void nsa_item(const Params& p, int l_, int item, char* lds, int dry) {
;     ...
;   for (int nb = 0; nb < 2; ++nb) {
;     const float lt = l[nb] + shx(l[nb], lane, 32);
;     const float sc = ((lt > 0.f) ? 1.f / lt : 0.f) * NSA_GATE(1, nb);
; #pragma unroll
;     for (int db = 0; db < 2; ++db)
; #pragma unroll
;       for (int i = 0; i < 2; ++i) {
;         uint4 o = scr[((nb * 2 + db) * 2 + i) * 256];
;         o.x = pk2(bflo(o.x) + O[db][nb][8 * i] * sc, bfhi(o.x) + O[db][nb][8 * i + 1] * sc);
;         o.y = pk2(bflo(o.y) + O[db][nb][8 * i + 2] * sc, bfhi(o.y) + O[db][nb][8 * i + 3] * sc);
;         o.z = pk2(bflo(o.z) + O[db][nb][8 * i + 4] * sc, bfhi(o.z) + O[db][nb][8 * i + 5] * sc);
;         o.w = pk2(bflo(o.w) + O[db][nb][8 * i + 6] * sc, bfhi(o.w) + O[db][nb][8 * i + 7] * sc);
;         scr[((nb * 2 + db) * 2 + i) * 256] = o;
;       }
.LBB0_748:
	ds_bpermute_b32 v0, v176, v80
	v_readlane_b32 s0, v254, 17
	s_lshl_b32 s2, s0, 6
	v_readlane_b32 s6, v253, 1
	v_readlane_b32 s7, v253, 2
	s_waitcnt lgkmcnt(0)
	v_add_f32_e32 v0, v80, v0
	v_div_scale_f32 v2, s[4:5], v0, v0, 1.0
	v_rcp_f32_e32 v3, v2
	v_cmp_lt_f32_e64 s[0:1], 0, v0
	v_fma_f32 v4, -v2, v3, 1.0
	v_fmac_f32_e32 v3, v4, v3
	v_div_scale_f32 v4, vcc, 1.0, v0, 1.0
	v_mul_f32_e32 v5, v4, v3
	v_fma_f32 v6, -v2, v5, v4
	v_fmac_f32_e32 v5, v6, v3
	v_fma_f32 v2, -v2, v5, v4
	v_div_fmas_f32 v2, v2, v3, v5
	v_div_fixup_f32 v0, v2, v0, 1.0
	global_load_ushort v2, v[174:175], off offset:544
	v_cndmask_b32_e64 v0, 0, v0, s[0:1]
	s_waitcnt vmcnt(0)
	v_mov_b32_e32 v228, v209
	v_ashrrev_i32_e32 v229, 31, v228
	v_lshl_add_u64 v[228:229], v[228:229], 4, s[6:7]
	global_load_dwordx4 v[84:87], v[228:229], off
	v_add_co_u32_e32 v230, vcc, 0x1000, v228
	s_nop 1
	v_addc_co_u32_e32 v231, vcc, 0, v229, vcc
	global_load_dwordx4 v[88:91], v[230:231], off
	v_add_co_u32_e32 v230, vcc, 0x2000, v228
	s_nop 1
	v_addc_co_u32_e32 v231, vcc, 0, v229, vcc
	global_load_dwordx4 v[92:95], v[230:231], off
	v_add_co_u32_e32 v230, vcc, 0x3000, v228
	s_nop 1
	v_addc_co_u32_e32 v231, vcc, 0, v229, vcc
	global_load_dwordx4 v[96:99], v[230:231], off
	global_load_ushort v236, v[170:171], off offset:544
	v_add_co_u32_e32 v230, vcc, 0x4000, v228
	s_nop 1
	v_addc_co_u32_e32 v231, vcc, 0, v229, vcc
	global_load_dwordx4 v[100:103], v[230:231], off
	v_add_co_u32_e32 v230, vcc, 0x5000, v228
	s_nop 1
	v_addc_co_u32_e32 v231, vcc, 0, v229, vcc
	global_load_dwordx4 v[104:107], v[230:231], off
	v_add_co_u32_e32 v230, vcc, 0x6000, v228
	s_nop 1
	v_addc_co_u32_e32 v231, vcc, 0, v229, vcc
	global_load_dwordx4 v[108:111], v[230:231], off
	v_add_co_u32_e32 v230, vcc, 0x7000, v228
	s_nop 1
	v_addc_co_u32_e32 v231, vcc, 0, v229, vcc
	global_load_dwordx4 v[232:235], v[230:231], off
	v_cvt_f32_f16_e32 v2, v2
	v_mul_f32_e32 v2, 0xbfb8aa3b, v2
	v_exp_f32_e32 v2, v2
	s_nop 0
	v_add_f32_e32 v2, 1.0, v2
	v_div_scale_f32 v3, s[0:1], v2, v2, 1.0
	v_rcp_f32_e32 v4, v3
	s_movk_i32 s0, 0x1000
	v_fma_f32 v5, -v3, v4, 1.0
	v_fmac_f32_e32 v4, v5, v4
	v_div_scale_f32 v5, vcc, 1.0, v2, 1.0
	v_mul_f32_e32 v6, v5, v4
	v_fma_f32 v7, -v3, v6, v5
	v_fmac_f32_e32 v6, v7, v4
	v_fma_f32 v3, -v3, v6, v5
	v_div_fmas_f32 v3, v3, v4, v6
	v_div_fixup_f32 v2, v3, v2, 1.0
	v_mul_f32_e32 v0, v0, v2
	v_mov_b32_e32 v2, v209
	s_nop 0
	v_ashrrev_i32_e32 v3, 31, v2
	v_lshl_add_u64 v[2:3], v[2:3], 4, s[6:7]
	s_waitcnt vmcnt(8)
	v_cvt_f32_f16_e32 v6, v84
	v_cvt_f32_f16_sdwa v7, v84 dst_sel:DWORD dst_unused:UNUSED_PAD src0_sel:WORD_1
	v_pk_fma_f32 v[6:7], v[64:65], v[0:1], v[6:7] op_sel_hi:[1,0,1]
	s_nop 0
	v_cvt_pk_f16_f32 v2, v6, v7
	v_cvt_f32_f16_e32 v6, v85
	v_cvt_f32_f16_sdwa v7, v85 dst_sel:DWORD dst_unused:UNUSED_PAD src0_sel:WORD_1
	v_pk_fma_f32 v[6:7], v[66:67], v[0:1], v[6:7] op_sel_hi:[1,0,1]
	s_nop 0
	v_cvt_pk_f16_f32 v3, v6, v7
	v_cvt_f32_f16_e32 v6, v86
	v_cvt_f32_f16_sdwa v7, v86 dst_sel:DWORD dst_unused:UNUSED_PAD src0_sel:WORD_1
	v_pk_fma_f32 v[6:7], v[68:69], v[0:1], v[6:7] op_sel_hi:[1,0,1]
	s_nop 0
	v_cvt_pk_f16_f32 v4, v6, v7
	v_cvt_f32_f16_e32 v6, v87
	v_cvt_f32_f16_sdwa v7, v87 dst_sel:DWORD dst_unused:UNUSED_PAD src0_sel:WORD_1
	v_pk_fma_f32 v[6:7], v[70:71], v[0:1], v[6:7] op_sel_hi:[1,0,1]
	s_nop 0
	v_cvt_pk_f16_f32 v5, v6, v7
	v_mov_b32_e32 v6, v209
	s_nop 0
	v_ashrrev_i32_e32 v7, 31, v6
	v_lshl_add_u64 v[6:7], v[6:7], 4, s[6:7]
	global_store_dwordx4 v[6:7], v[2:5], off
	s_nop 1
	v_mov_b32_e32 v2, v209
	s_nop 0
	v_ashrrev_i32_e32 v3, 31, v2
	v_lshl_add_u64 v[2:3], v[2:3], 4, s[6:7]
	v_add_co_u32_e32 v2, vcc, s0, v2
	s_nop 1
	v_addc_co_u32_e32 v3, vcc, 0, v3, vcc
	s_waitcnt vmcnt(8)
	v_cvt_f32_f16_e32 v6, v88
	v_cvt_f32_f16_sdwa v7, v88 dst_sel:DWORD dst_unused:UNUSED_PAD src0_sel:WORD_1
	v_pk_fma_f32 v[6:7], v[72:73], v[0:1], v[6:7] op_sel_hi:[1,0,1]
	s_nop 0
	v_cvt_pk_f16_f32 v2, v6, v7
	v_cvt_f32_f16_e32 v6, v89
	v_cvt_f32_f16_sdwa v7, v89 dst_sel:DWORD dst_unused:UNUSED_PAD src0_sel:WORD_1
	v_pk_fma_f32 v[6:7], v[74:75], v[0:1], v[6:7] op_sel_hi:[1,0,1]
	s_nop 0
	v_cvt_pk_f16_f32 v3, v6, v7
	v_cvt_f32_f16_e32 v6, v90
	v_cvt_f32_f16_sdwa v7, v90 dst_sel:DWORD dst_unused:UNUSED_PAD src0_sel:WORD_1
	v_pk_fma_f32 v[6:7], v[76:77], v[0:1], v[6:7] op_sel_hi:[1,0,1]
	s_nop 0
	v_cvt_pk_f16_f32 v4, v6, v7
	v_cvt_f32_f16_e32 v6, v91
	v_cvt_f32_f16_sdwa v7, v91 dst_sel:DWORD dst_unused:UNUSED_PAD src0_sel:WORD_1
	v_pk_fma_f32 v[6:7], v[78:79], v[0:1], v[6:7] op_sel_hi:[1,0,1]
	s_nop 0
	v_cvt_pk_f16_f32 v5, v6, v7
	v_mov_b32_e32 v6, v209
	s_nop 0
	v_ashrrev_i32_e32 v7, 31, v6
	v_lshl_add_u64 v[6:7], v[6:7], 4, s[6:7]
	v_add_co_u32_e32 v6, vcc, s0, v6
	s_movk_i32 s0, 0x2000
	s_nop 0
	v_addc_co_u32_e32 v7, vcc, 0, v7, vcc
	global_store_dwordx4 v[6:7], v[2:5], off
	s_nop 1
	v_mov_b32_e32 v2, v209
	s_nop 0
	v_ashrrev_i32_e32 v3, 31, v2
	v_lshl_add_u64 v[2:3], v[2:3], 4, s[6:7]
	v_add_co_u32_e32 v2, vcc, s0, v2
	s_nop 1
	v_addc_co_u32_e32 v3, vcc, 0, v3, vcc
	s_waitcnt vmcnt(8)
; DI unsigned pk2(float a, float b) { f2_t v = {a, b}; bf2_t r = __builtin_convertvector(v, bf2_t); return __builtin_bit_cast(unsigned, r); }
; DI float bflo(unsigned u) { return (float)__builtin_bit_cast(bf2_t, u)[0]; }
; DI float bfhi(unsigned u) { return (float)__builtin_bit_cast(bf2_t, u)[1]; }
; #define NSA_GATE(c_, nb_) sigmoidf_(bf2f(zb[(size_t)qpos[nb_] * ZS + GATEC + (c_) * 8 + head]))
; DI void nsa_item(const Params& p, int l_, int item, char* lds, int dry) {
;     ...
;   for (int nb = 0; nb < 2; ++nb) {
;     const float lt = l[nb] + shx(l[nb], lane, 32);
;     const float sc = ((lt > 0.f) ? 1.f / lt : 0.f) * NSA_GATE(1, nb);
; #pragma unroll
;     for (int db = 0; db < 2; ++db)
; #pragma unroll
;       for (int i = 0; i < 2; ++i) {
;         uint4 o = scr[((nb * 2 + db) * 2 + i) * 256];
;         o.x = pk2(bflo(o.x) + O[db][nb][8 * i] * sc, bfhi(o.x) + O[db][nb][8 * i + 1] * sc);
;         o.y = pk2(bflo(o.y) + O[db][nb][8 * i + 2] * sc, bfhi(o.y) + O[db][nb][8 * i + 3] * sc);
;         o.z = pk2(bflo(o.z) + O[db][nb][8 * i + 4] * sc, bfhi(o.z) + O[db][nb][8 * i + 5] * sc);
;         o.w = pk2(bflo(o.w) + O[db][nb][8 * i + 6] * sc, bfhi(o.w) + O[db][nb][8 * i + 7] * sc);
;         scr[((nb * 2 + db) * 2 + i) * 256] = o;
;       }
	v_cvt_f32_f16_e32 v6, v92
	v_cvt_f32_f16_sdwa v7, v92 dst_sel:DWORD dst_unused:UNUSED_PAD src0_sel:WORD_1
	v_pk_fma_f32 v[6:7], v[48:49], v[0:1], v[6:7] op_sel_hi:[1,0,1]
	s_nop 0
	v_cvt_pk_f16_f32 v2, v6, v7
	v_cvt_f32_f16_e32 v6, v93
	v_cvt_f32_f16_sdwa v7, v93 dst_sel:DWORD dst_unused:UNUSED_PAD src0_sel:WORD_1
	v_pk_fma_f32 v[6:7], v[50:51], v[0:1], v[6:7] op_sel_hi:[1,0,1]
	s_nop 0
	v_cvt_pk_f16_f32 v3, v6, v7
	v_cvt_f32_f16_e32 v6, v94
	v_cvt_f32_f16_sdwa v7, v94 dst_sel:DWORD dst_unused:UNUSED_PAD src0_sel:WORD_1
	v_pk_fma_f32 v[6:7], v[52:53], v[0:1], v[6:7] op_sel_hi:[1,0,1]
	s_nop 0
	v_cvt_pk_f16_f32 v4, v6, v7
	v_cvt_f32_f16_e32 v6, v95
	v_cvt_f32_f16_sdwa v7, v95 dst_sel:DWORD dst_unused:UNUSED_PAD src0_sel:WORD_1
	v_pk_fma_f32 v[6:7], v[54:55], v[0:1], v[6:7] op_sel_hi:[1,0,1]
	s_nop 0
	v_cvt_pk_f16_f32 v5, v6, v7
	v_mov_b32_e32 v6, v209
	s_nop 0
	v_ashrrev_i32_e32 v7, 31, v6
	v_lshl_add_u64 v[6:7], v[6:7], 4, s[6:7]
	v_add_co_u32_e32 v6, vcc, s0, v6
	s_movk_i32 s0, 0x3000
	s_nop 0
	v_addc_co_u32_e32 v7, vcc, 0, v7, vcc
	global_store_dwordx4 v[6:7], v[2:5], off
	s_nop 1
	v_mov_b32_e32 v2, v209
	s_nop 0
	v_ashrrev_i32_e32 v3, 31, v2
	v_lshl_add_u64 v[2:3], v[2:3], 4, s[6:7]
	v_add_co_u32_e32 v2, vcc, s0, v2
	s_nop 1
	v_addc_co_u32_e32 v3, vcc, 0, v3, vcc
	s_waitcnt vmcnt(8)
	v_cvt_f32_f16_e32 v6, v96
	v_cvt_f32_f16_sdwa v7, v96 dst_sel:DWORD dst_unused:UNUSED_PAD src0_sel:WORD_1
	v_pk_fma_f32 v[6:7], v[56:57], v[0:1], v[6:7] op_sel_hi:[1,0,1]
	s_nop 0
	v_cvt_pk_f16_f32 v2, v6, v7
	v_cvt_f32_f16_e32 v6, v97
	v_cvt_f32_f16_sdwa v7, v97 dst_sel:DWORD dst_unused:UNUSED_PAD src0_sel:WORD_1
	v_pk_fma_f32 v[6:7], v[58:59], v[0:1], v[6:7] op_sel_hi:[1,0,1]
	s_nop 0
	v_cvt_pk_f16_f32 v3, v6, v7
	v_cvt_f32_f16_e32 v6, v98
	v_cvt_f32_f16_sdwa v7, v98 dst_sel:DWORD dst_unused:UNUSED_PAD src0_sel:WORD_1
	v_pk_fma_f32 v[6:7], v[60:61], v[0:1], v[6:7] op_sel_hi:[1,0,1]
	s_nop 0
	v_cvt_pk_f16_f32 v4, v6, v7
	v_cvt_f32_f16_e32 v6, v99
	v_cvt_f32_f16_sdwa v7, v99 dst_sel:DWORD dst_unused:UNUSED_PAD src0_sel:WORD_1
	v_pk_fma_f32 v[6:7], v[62:63], v[0:1], v[6:7] op_sel_hi:[1,0,1]
	ds_bpermute_b32 v0, v176, v180
	v_cvt_pk_f16_f32 v5, v6, v7
	v_mov_b32_e32 v6, v209
	s_waitcnt lgkmcnt(0)
	v_add_f32_e32 v0, v180, v0
	v_ashrrev_i32_e32 v7, 31, v6
	v_lshl_add_u64 v[6:7], v[6:7], 4, s[6:7]
	v_add_co_u32_e32 v6, vcc, s0, v6
	v_cmp_lt_f32_e64 s[0:1], 0, v0
	s_nop 0
	v_addc_co_u32_e32 v7, vcc, 0, v7, vcc
	global_store_dwordx4 v[6:7], v[2:5], off
	s_nop 1
	v_div_scale_f32 v2, s[4:5], v0, v0, 1.0
	v_rcp_f32_e32 v3, v2
	s_nop 0
	v_fma_f32 v4, -v2, v3, 1.0
	v_fmac_f32_e32 v3, v4, v3
	v_div_scale_f32 v4, vcc, 1.0, v0, 1.0
	v_mul_f32_e32 v5, v4, v3
	v_fma_f32 v6, -v2, v5, v4
	v_fmac_f32_e32 v5, v6, v3
	v_fma_f32 v2, -v2, v5, v4
	v_div_fmas_f32 v2, v2, v3, v5
	v_div_fixup_f32 v0, v2, v0, 1.0
	v_cndmask_b32_e64 v0, 0, v0, s[0:1]
	s_waitcnt vmcnt(8)
	v_cvt_f32_f16_e32 v2, v236
	v_mul_f32_e32 v2, 0xbfb8aa3b, v2
	v_exp_f32_e32 v2, v2
	s_nop 0
	v_add_f32_e32 v2, 1.0, v2
	v_div_scale_f32 v3, s[0:1], v2, v2, 1.0
	v_rcp_f32_e32 v4, v3
	s_movk_i32 s0, 0x4000
	v_readlane_b32 s1, v254, 16
	v_fma_f32 v5, -v3, v4, 1.0
	v_fmac_f32_e32 v4, v5, v4
	v_div_scale_f32 v5, vcc, 1.0, v2, 1.0
	v_mul_f32_e32 v6, v5, v4
	v_fma_f32 v7, -v3, v6, v5
	v_fmac_f32_e32 v6, v7, v4
	v_fma_f32 v3, -v3, v6, v5
	v_div_fmas_f32 v3, v3, v4, v6
	v_div_fixup_f32 v2, v3, v2, 1.0
	v_mul_f32_e32 v0, v0, v2
	v_mov_b32_e32 v2, v209
	s_nop 0
	v_ashrrev_i32_e32 v3, 31, v2
	v_lshl_add_u64 v[2:3], v[2:3], 4, s[6:7]
	v_add_co_u32_e32 v2, vcc, s0, v2
	s_nop 1
	v_addc_co_u32_e32 v3, vcc, 0, v3, vcc
	s_waitcnt vmcnt(7)
	v_cvt_f32_f16_e32 v6, v100
	v_cvt_f32_f16_sdwa v7, v100 dst_sel:DWORD dst_unused:UNUSED_PAD src0_sel:WORD_1
	v_pk_fma_f32 v[6:7], v[32:33], v[0:1], v[6:7] op_sel_hi:[1,0,1]
	s_nop 0
	v_cvt_pk_f16_f32 v2, v6, v7
	v_cvt_f32_f16_e32 v6, v101
	v_cvt_f32_f16_sdwa v7, v101 dst_sel:DWORD dst_unused:UNUSED_PAD src0_sel:WORD_1
	v_pk_fma_f32 v[6:7], v[34:35], v[0:1], v[6:7] op_sel_hi:[1,0,1]
	s_nop 0
	v_cvt_pk_f16_f32 v3, v6, v7
	v_cvt_f32_f16_e32 v6, v102
	v_cvt_f32_f16_sdwa v7, v102 dst_sel:DWORD dst_unused:UNUSED_PAD src0_sel:WORD_1
	v_pk_fma_f32 v[6:7], v[36:37], v[0:1], v[6:7] op_sel_hi:[1,0,1]
	s_nop 0
	v_cvt_pk_f16_f32 v4, v6, v7
	v_cvt_f32_f16_e32 v6, v103
	v_cvt_f32_f16_sdwa v7, v103 dst_sel:DWORD dst_unused:UNUSED_PAD src0_sel:WORD_1
	v_pk_fma_f32 v[6:7], v[38:39], v[0:1], v[6:7] op_sel_hi:[1,0,1]
	s_nop 0
	v_cvt_pk_f16_f32 v5, v6, v7
	v_mov_b32_e32 v6, v209
	s_nop 0
	v_ashrrev_i32_e32 v7, 31, v6
	v_lshl_add_u64 v[6:7], v[6:7], 4, s[6:7]
	v_add_co_u32_e32 v6, vcc, s0, v6
	s_movk_i32 s0, 0x5000
	s_nop 0
	v_addc_co_u32_e32 v7, vcc, 0, v7, vcc
	global_store_dwordx4 v[6:7], v[2:5], off
	s_nop 1
	v_mov_b32_e32 v2, v209
	s_nop 0
	v_ashrrev_i32_e32 v3, 31, v2
	v_lshl_add_u64 v[2:3], v[2:3], 4, s[6:7]
	v_add_co_u32_e32 v2, vcc, s0, v2
	s_nop 1
	v_addc_co_u32_e32 v3, vcc, 0, v3, vcc
	s_waitcnt vmcnt(7)
	v_cvt_f32_f16_e32 v6, v104
	v_cvt_f32_f16_sdwa v7, v104 dst_sel:DWORD dst_unused:UNUSED_PAD src0_sel:WORD_1
	v_pk_fma_f32 v[6:7], v[40:41], v[0:1], v[6:7] op_sel_hi:[1,0,1]
	s_nop 0
	v_cvt_pk_f16_f32 v2, v6, v7
	v_cvt_f32_f16_e32 v6, v105
	v_cvt_f32_f16_sdwa v7, v105 dst_sel:DWORD dst_unused:UNUSED_PAD src0_sel:WORD_1
	v_pk_fma_f32 v[6:7], v[42:43], v[0:1], v[6:7] op_sel_hi:[1,0,1]
	s_nop 0
	v_cvt_pk_f16_f32 v3, v6, v7
	v_cvt_f32_f16_e32 v6, v106
	v_cvt_f32_f16_sdwa v7, v106 dst_sel:DWORD dst_unused:UNUSED_PAD src0_sel:WORD_1
	v_pk_fma_f32 v[6:7], v[44:45], v[0:1], v[6:7] op_sel_hi:[1,0,1]
	s_nop 0
	v_cvt_pk_f16_f32 v4, v6, v7
	v_cvt_f32_f16_e32 v6, v107
	v_cvt_f32_f16_sdwa v7, v107 dst_sel:DWORD dst_unused:UNUSED_PAD src0_sel:WORD_1
	v_pk_fma_f32 v[6:7], v[46:47], v[0:1], v[6:7] op_sel_hi:[1,0,1]
	s_nop 0
	v_cvt_pk_f16_f32 v5, v6, v7
	v_mov_b32_e32 v6, v209
	s_nop 0
	v_ashrrev_i32_e32 v7, 31, v6
	v_lshl_add_u64 v[6:7], v[6:7], 4, s[6:7]
	v_add_co_u32_e32 v6, vcc, s0, v6
	s_movk_i32 s0, 0x6000
	s_nop 0
	v_addc_co_u32_e32 v7, vcc, 0, v7, vcc
	global_store_dwordx4 v[6:7], v[2:5], off
	s_nop 1
	v_mov_b32_e32 v2, v209
	s_nop 0
	v_ashrrev_i32_e32 v3, 31, v2
	v_lshl_add_u64 v[2:3], v[2:3], 4, s[6:7]
	v_add_co_u32_e32 v2, vcc, s0, v2
	s_nop 1
	v_addc_co_u32_e32 v3, vcc, 0, v3, vcc
	s_waitcnt vmcnt(7)
; DI unsigned pk2(float a, float b) { f2_t v = {a, b}; bf2_t r = __builtin_convertvector(v, bf2_t); return __builtin_bit_cast(unsigned, r); }
; DI float bflo(unsigned u) { return (float)__builtin_bit_cast(bf2_t, u)[0]; }
; DI float bfhi(unsigned u) { return (float)__builtin_bit_cast(bf2_t, u)[1]; }
; template <int MODE> ...
;     ...
;   ALOAD(0);
;   ASTORE(0);
;   __syncthreads();
; DI void nsa_item(const Params& p, int l_, int item, char* lds, int dry) {
;     ...
;     for (int db = 0; db < 2; ++db)
; #pragma unroll
;       for (int i = 0; i < 2; ++i) {
;         uint4 o = scr[((nb * 2 + db) * 2 + i) * 256];
;         o.x = pk2(bflo(o.x) + O[db][nb][8 * i] * sc, bfhi(o.x) + O[db][nb][8 * i + 1] * sc);
;         o.y = pk2(bflo(o.y) + O[db][nb][8 * i + 2] * sc, bfhi(o.y) + O[db][nb][8 * i + 3] * sc);
;         o.z = pk2(bflo(o.z) + O[db][nb][8 * i + 4] * sc, bfhi(o.z) + O[db][nb][8 * i + 5] * sc);
;         o.w = pk2(bflo(o.w) + O[db][nb][8 * i + 6] * sc, bfhi(o.w) + O[db][nb][8 * i + 7] * sc);
;         scr[((nb * 2 + db) * 2 + i) * 256] = o;
;       }
;   }
;   attn_init(O, m, l);
;   const int first = (qb >= 8) ? qb - 8 : 0;
;   attn_run<M_WIN>(lds, zb + KWC + g * 64, zb + VWC + g * 64, ZS, nullptr, qb - first + 1, first, qf, O, m, l, qpos, cq, selb, linv, wq0);
	v_cvt_f32_f16_e32 v6, v108
	v_cvt_f32_f16_sdwa v7, v108 dst_sel:DWORD dst_unused:UNUSED_PAD src0_sel:WORD_1
	v_pk_fma_f32 v[6:7], v[16:17], v[0:1], v[6:7] op_sel_hi:[1,0,1]
	s_nop 0
	v_cvt_pk_f16_f32 v2, v6, v7
	v_cvt_f32_f16_e32 v6, v109
	v_cvt_f32_f16_sdwa v7, v109 dst_sel:DWORD dst_unused:UNUSED_PAD src0_sel:WORD_1
	v_pk_fma_f32 v[6:7], v[18:19], v[0:1], v[6:7] op_sel_hi:[1,0,1]
	s_nop 0
	v_cvt_pk_f16_f32 v3, v6, v7
	v_cvt_f32_f16_e32 v6, v110
	v_cvt_f32_f16_sdwa v7, v110 dst_sel:DWORD dst_unused:UNUSED_PAD src0_sel:WORD_1
	v_pk_fma_f32 v[6:7], v[20:21], v[0:1], v[6:7] op_sel_hi:[1,0,1]
	s_nop 0
	v_cvt_pk_f16_f32 v4, v6, v7
	v_cvt_f32_f16_e32 v6, v111
	v_cvt_f32_f16_sdwa v7, v111 dst_sel:DWORD dst_unused:UNUSED_PAD src0_sel:WORD_1
	v_pk_fma_f32 v[6:7], v[22:23], v[0:1], v[6:7] op_sel_hi:[1,0,1]
	s_nop 0
	v_cvt_pk_f16_f32 v5, v6, v7
	v_mov_b32_e32 v6, v209
	s_nop 0
	v_ashrrev_i32_e32 v7, 31, v6
	v_lshl_add_u64 v[6:7], v[6:7], 4, s[6:7]
	v_add_co_u32_e32 v6, vcc, s0, v6
	s_movk_i32 s0, 0x7000
	s_nop 0
	v_addc_co_u32_e32 v7, vcc, 0, v7, vcc
	global_store_dwordx4 v[6:7], v[2:5], off
	s_nop 1
	v_mov_b32_e32 v2, v209
	s_nop 0
	v_ashrrev_i32_e32 v3, 31, v2
	v_lshl_add_u64 v[2:3], v[2:3], 4, s[6:7]
	v_add_co_u32_e32 v2, vcc, s0, v2
	s_nop 1
	v_addc_co_u32_e32 v3, vcc, 0, v3, vcc
	s_waitcnt vmcnt(7)
	v_cvt_f32_f16_e32 v6, v232
	v_cvt_f32_f16_sdwa v7, v232 dst_sel:DWORD dst_unused:UNUSED_PAD src0_sel:WORD_1
	v_pk_fma_f32 v[6:7], v[24:25], v[0:1], v[6:7] op_sel_hi:[1,0,1]
	s_nop 0
	v_cvt_pk_f16_f32 v2, v6, v7
	v_cvt_f32_f16_e32 v6, v233
	v_cvt_f32_f16_sdwa v7, v233 dst_sel:DWORD dst_unused:UNUSED_PAD src0_sel:WORD_1
	v_pk_fma_f32 v[6:7], v[26:27], v[0:1], v[6:7] op_sel_hi:[1,0,1]
	s_nop 0
	v_cvt_pk_f16_f32 v3, v6, v7
	v_cvt_f32_f16_e32 v6, v234
	v_cvt_f32_f16_sdwa v7, v234 dst_sel:DWORD dst_unused:UNUSED_PAD src0_sel:WORD_1
	v_pk_fma_f32 v[6:7], v[28:29], v[0:1], v[6:7] op_sel_hi:[1,0,1]
	s_nop 0
	v_cvt_pk_f16_f32 v4, v6, v7
	v_cvt_f32_f16_e32 v6, v235
	v_cvt_f32_f16_sdwa v7, v235 dst_sel:DWORD dst_unused:UNUSED_PAD src0_sel:WORD_1
	v_pk_fma_f32 v[6:7], v[30:31], v[0:1], v[6:7] op_sel_hi:[1,0,1]
	s_nop 0
	v_cvt_pk_f16_f32 v5, v6, v7
	v_mov_b32_e32 v6, v209
	s_nop 0
	v_ashrrev_i32_e32 v7, 31, v6
	v_lshl_add_u64 v[6:7], v[6:7], 4, s[6:7]
	v_add_co_u32_e32 v6, vcc, s0, v6
	s_sub_i32 s0, 55, s1
	s_nop 0
	v_addc_co_u32_e32 v7, vcc, 0, v7, vcc
	s_cmp_lt_i32 s1, 56
	global_store_dwordx4 v[6:7], v[2:5], off
	s_cselect_b32 s12, s0, 0
	s_lshl_b32 s0, s2, 1
	v_readlane_b32 s2, v254, 18
	v_mov_b32_e32 v3, v209
	v_readlane_b32 s3, v254, 19
	s_add_u32 s0, s2, s0
	s_addc_u32 s1, s3, 0
	v_ashrrev_i32_e32 v165, 3, v3
	v_lshl_add_u32 v0, s12, 6, v165
	v_lshlrev_b32_e32 v2, 3, v3
	s_add_u32 s4, s0, 0x2000
	v_mul_lo_u32 v0, v0, s54
	v_and_b32_e32 v166, 56, v2
	s_addc_u32 s5, s1, 0
	v_or_b32_e32 v0, v0, v166
	s_add_u32 s6, s0, 0x2100
	v_add_u32_e32 v4, 0x33000, v0
	v_lshlrev_b64 v[6:7], 1, v[0:1]
	v_mov_b32_e32 v5, v1
	s_addc_u32 s7, s1, 0
	v_lshl_add_u64 v[8:9], s[4:5], 0, v[6:7]
	v_lshlrev_b64 v[4:5], 1, v[4:5]
	global_load_dwordx4 v[144:147], v[8:9], off
	v_lshl_add_u64 v[8:9], s[4:5], 0, v[4:5]
	v_lshl_add_u64 v[6:7], s[6:7], 0, v[6:7]
	v_lshl_add_u64 v[4:5], s[6:7], 0, v[4:5]
	global_load_dwordx4 v[148:151], v[8:9], off
	global_load_dwordx4 v[152:155], v[6:7], off
	global_load_dwordx4 v[156:159], v[4:5], off
	v_readlane_b32 s0, v254, 20
	s_sub_i32 s13, s0, s12
	v_mul_lo_u32 v0, v165, s76
	v_lshl_add_u32 v167, v166, 1, v0
	s_cmp_lt_i32 s13, 0
	s_waitcnt vmcnt(3)
	ds_write_b128 v167, v[144:147]
	s_waitcnt vmcnt(2)
	ds_write_b128 v167, v[148:151] offset:4608
	s_waitcnt vmcnt(1)
	ds_write_b128 v167, v[152:155] offset:18432
	s_waitcnt vmcnt(0)
	ds_write_b128 v167, v[156:159] offset:23040
	s_waitcnt lgkmcnt(0)
	s_barrier
	s_cbranch_scc1 .LBB0_768
	v_and_b32_e32 v180, 31, v3
	v_and_b32_e32 v0, 16, v3
	v_lshrrev_b32_e32 v4, 2, v3
	v_and_b32_e32 v5, 63, v3
	v_bfe_u32 v3, v3, 5, 1
	v_lshlrev_b32_e32 v5, 2, v5
	v_lshlrev_b32_e32 v183, 2, v3
	v_and_b32_e32 v2, 24, v2
	v_mov_b32_e32 v14, v1
	v_mov_b32_e32 v15, v1
	v_lshlrev_b32_e32 v181, 4, v3
	v_xor_b32_e32 v182, 0x80, v5
	v_and_or_b32 v184, v4, 3, v183
	v_lshl_or_b32 v185, v0, 1, v2
	v_mov_b32_e32 v0, v1
	v_mov_b32_e32 v2, v1
	v_mov_b32_e32 v3, v1
	v_mov_b32_e32 v4, v1
	v_mov_b32_e32 v5, v1
	v_mov_b32_e32 v6, v1
	v_mov_b32_e32 v7, v1
	v_mov_b32_e32 v8, v1
	v_mov_b32_e32 v9, v1
	v_mov_b32_e32 v10, v1
	v_mov_b32_e32 v11, v1
	v_mov_b32_e32 v12, v1
	v_mov_b32_e32 v13, v1
	v_mov_b64_e32 v[30:31], v[14:15]
	v_mov_b64_e32 v[62:63], v[14:15]
	v_mov_b64_e32 v[46:47], v[14:15]
	v_mov_b64_e32 v[78:79], v[14:15]
	s_or_b32 s14, s77, 63
	s_add_i32 s15, s77, 0xfffffe00
	s_add_i32 s16, s77, 0xfffffe3f
	v_add_u32_e32 v186, 0xfffffe00, v178
	v_add_u32_e32 v187, 0xfffffe20, v178
	s_mov_b32 s17, 0
	v_mov_b32_e32 v188, 0xf149f2ca
	v_mov_b32_e32 v164, 0
	v_mov_b64_e32 v[28:29], v[12:13]
	v_mov_b64_e32 v[26:27], v[10:11]
	v_mov_b64_e32 v[24:25], v[8:9]
	v_mov_b64_e32 v[22:23], v[6:7]
	v_mov_b64_e32 v[20:21], v[4:5]
	v_mov_b64_e32 v[18:19], v[2:3]
	v_mov_b64_e32 v[16:17], v[0:1]
	v_mov_b64_e32 v[60:61], v[12:13]
	v_mov_b64_e32 v[58:59], v[10:11]
	v_mov_b64_e32 v[56:57], v[8:9]
	v_mov_b64_e32 v[54:55], v[6:7]
	v_mov_b64_e32 v[52:53], v[4:5]
	v_mov_b64_e32 v[50:51], v[2:3]
	v_mov_b64_e32 v[48:49], v[0:1]
	v_mov_b64_e32 v[44:45], v[12:13]
	v_mov_b64_e32 v[42:43], v[10:11]
	v_mov_b64_e32 v[40:41], v[8:9]
	v_mov_b64_e32 v[38:39], v[6:7]
	v_mov_b64_e32 v[36:37], v[4:5]
	v_mov_b64_e32 v[34:35], v[2:3]
	v_mov_b64_e32 v[32:33], v[0:1]
	v_mov_b64_e32 v[76:77], v[12:13]
	v_mov_b64_e32 v[74:75], v[10:11]
	v_mov_b64_e32 v[72:73], v[8:9]
	v_mov_b64_e32 v[70:71], v[6:7]
	v_mov_b64_e32 v[68:69], v[4:5]
	v_mov_b64_e32 v[66:67], v[2:3]
	v_mov_b64_e32 v[64:65], v[0:1]
	v_mov_b32_e32 v2, 0
	v_mov_b32_e32 v15, 0xf149f2ca
	v_mov_b32_e32 v14, 0
